# phase A rmsnorm rows: next row prefetched into spare registers while the current row is reduced and stored
# speedup vs baseline: 1.0469x; 1.0021x over previous
; __device__ __forceinline__ unsigned pk2(float lo, float hi) { f32x2_t v = {lo, hi}; bf16x2_t b = __builtin_convertvector(v, bf16x2_t); return __builtin_bit_cast(unsigned, b); }
; __device__ __forceinline__ float wave_sum(float v) { v += __shfl_xor(v, 1); v += __shfl_xor(v, 2); v += __shfl_xor(v, 4); v += __shfl_xor(v, 8); v += __shfl_xor(v, 16); v += __shfl_xor(v, 32); return v; }
; __device__ __forceinline__ void rmsnorm_rows(const float* __restrict__ x, const float* __restrict__ g, bf16_t* __restrict__ h, int gwave, int nwaves, int lane) {
;     for (int row = gwave; row < MTOK; row += nwaves) {
;         const f32x4* xr = (const f32x4*)(x + (size_t)row * DM); f32x4 v[4]; float ss = 0.f;
; #pragma unroll
;         for (int i = 0; i < 4; ++i) { v[i] = xr[lane + 64 * i]; ss += v[i][0] * v[i][0] + v[i][1] * v[i][1] + v[i][2] * v[i][2] + v[i][3] * v[i][3]; }
;         ss = wave_sum(ss); const float rs = __builtin_amdgcn_rsqf(ss * (1.0f / DM) + 1e-6f);
; #pragma unroll
;         for (int i = 0; i < 4; ++i) { const f32x4 gv = ((const f32x4*)g)[lane + 64 * i]; u32x2 w; w.x = pk2(v[i][0] * rs * gv[0], v[i][1] * rs * gv[1]); w.y = pk2(v[i][2] * rs * gv[2], v[i][3] * rs * gv[3]);
;             *(u32x2*)(h + (size_t)row * DM + (lane + 64 * i) * 4) = w; }
;     }
; }
.LBB0_387:
	s_ashr_i32 s4, s28, 6
	s_lshl_b32 s5, s26, 3
	s_add_i32 s4, s4, s5
	s_and_b64 vcc, exec, s[12:13]
	s_cbranch_vccz .LBB0_391
	s_mov_b32 s18, s77
	s_mov_b32 s16, 2
	s_cmpk_gt_i32 s4, 0x7fff
	s_cbranch_scc1 .LBB0_391
	s_ashr_i32 s19, s18, 31
	s_lshl_b64 s[18:19], s[18:19], 3
	s_add_u32 s18, s0, s18
	s_addc_u32 s19, s1, s19
	s_ashr_i32 s17, s16, 31
	s_lshl_b64 s[16:17], s[16:17], 3
	s_add_u32 s16, s0, s16
	s_addc_u32 s17, s1, s17
	s_load_dwordx2 s[16:17], s[16:17], 0x0
	v_lshlrev_b32_e32 v80, 4, v33
	s_load_dwordx2 s[20:21], s[18:19], 0x0
	v_and_b32_e32 v17, 64, v195
	s_waitcnt lgkmcnt(0)
	global_load_dwordx4 v[0:3], v80, s[16:17]
	global_load_dwordx4 v[4:7], v80, s[16:17] offset:1024
	global_load_dwordx4 v[8:11], v80, s[16:17] offset:2048
	global_load_dwordx4 v[12:15], v80, s[16:17] offset:3072
	v_xor_b32_e32 v16, 1, v195
	v_add_u32_e32 v17, 64, v17
	v_cmp_lt_i32_e32 vcc, v16, v17
	s_ashr_i32 s5, s4, 31
	s_lshl_b32 s16, s27, 3
	v_cndmask_b32_e32 v16, v195, v16, vcc
	v_lshlrev_b32_e32 v38, 2, v16
	v_xor_b32_e32 v16, 2, v195
	v_cmp_lt_i32_e32 vcc, v16, v17
	s_lshl_b64 s[18:19], s[4:5], 11
	s_add_u32 s18, s8, s18
	v_cndmask_b32_e32 v16, v195, v16, vcc
	v_lshlrev_b32_e32 v39, 2, v16
	v_xor_b32_e32 v16, 4, v195
	v_cmp_lt_i32_e32 vcc, v16, v17
	s_addc_u32 s19, s9, s19
	s_ashr_i32 s17, s16, 31
	v_cndmask_b32_e32 v16, v195, v16, vcc
	v_lshlrev_b32_e32 v40, 2, v16
	v_xor_b32_e32 v16, 8, v195
	v_cmp_lt_i32_e32 vcc, v16, v17
	s_lshl_b64 s[22:23], s[4:5], 12
	s_mov_b32 s5, s4
	v_cndmask_b32_e32 v16, v195, v16, vcc
	v_lshlrev_b32_e32 v41, 2, v16
	v_xor_b32_e32 v16, 16, v195
	v_cmp_lt_i32_e32 vcc, v16, v17
	s_nop 1
	v_cndmask_b32_e32 v16, v195, v16, vcc
	v_lshlrev_b32_e32 v42, 2, v16
	v_xor_b32_e32 v16, 32, v195
	v_cmp_lt_i32_e32 vcc, v16, v17
	v_mov_b32_e32 v17, v81
	s_nop 0
	v_cndmask_b32_e32 v16, v195, v16, vcc
	v_lshlrev_b32_e32 v43, 2, v16
	v_lshlrev_b32_e32 v16, 3, v33
	v_lshl_add_u64 v[16:17], s[18:19], 0, v[16:17]
	s_mov_b64 s[18:19], 0x3100000
	v_lshl_add_u64 v[34:35], v[16:17], 0, s[18:19]
	s_lshl_b64 s[18:19], s[16:17], 11
	s_add_u32 s20, s20, s22
	s_addc_u32 s21, s21, s23
	v_lshl_add_u64 v[16:17], s[20:21], 0, v[80:81]
	s_mov_b64 s[20:21], 0xc00
	v_lshl_add_u64 v[36:37], v[16:17], 0, s[20:21]
	s_lshl_b64 s[20:21], s[16:17], 12
	global_load_dwordx4 v[54:57], v[36:37], off offset:-3072
	global_load_dwordx4 v[58:61], v[36:37], off offset:-2048
	global_load_dwordx4 v[62:65], v[36:37], off offset:-1024
	global_load_dwordx4 v[66:69], v[36:37], off
	s_waitcnt vmcnt(0)
.LBB0_390:
	s_waitcnt vmcnt(4)
	v_mov_b64_e32 v[16:17], v[54:55]
	v_mov_b64_e32 v[18:19], v[56:57]
	v_mov_b64_e32 v[20:21], v[58:59]
	v_mov_b64_e32 v[22:23], v[60:61]
	v_mov_b64_e32 v[28:29], v[62:63]
	v_mov_b64_e32 v[30:31], v[64:65]
	v_mov_b64_e32 v[24:25], v[66:67]
	v_mov_b64_e32 v[26:27], v[68:69]
	s_add_i32 s5, s5, s16
	v_lshl_add_u64 v[36:37], v[36:37], 0, s[20:21]
	s_cmp_lt_i32 s5, 0x8000
	s_cbranch_scc0 .Lrn_nopf
	global_load_dwordx4 v[54:57], v[36:37], off offset:-3072
	global_load_dwordx4 v[58:61], v[36:37], off offset:-2048
	global_load_dwordx4 v[62:65], v[36:37], off offset:-1024
	global_load_dwordx4 v[66:69], v[36:37], off
.Lrn_nopf:
	v_mul_f32_e32 v52, v17, v17
	v_mul_f32_e32 v53, v21, v21
	v_mov_b32_e32 v46, v29
	v_mov_b32_e32 v47, v25
	v_mov_b32_e32 v44, v28
	v_mov_b32_e32 v45, v24
	v_fmac_f32_e32 v52, v16, v16
	v_fmac_f32_e32 v53, v20, v20
	v_pk_mul_f32 v[46:47], v[46:47], v[46:47]
	v_mov_b32_e32 v48, v30
	v_mov_b32_e32 v49, v26
	v_fmac_f32_e32 v52, v18, v18
	v_fmac_f32_e32 v53, v22, v22
	v_pk_fma_f32 v[44:45], v[44:45], v[44:45], v[46:47]
	v_mov_b32_e32 v50, v31
	v_mov_b32_e32 v51, v27
	v_fmac_f32_e32 v52, v19, v19
	v_fmac_f32_e32 v53, v23, v23
	v_pk_fma_f32 v[44:45], v[48:49], v[48:49], v[44:45]
	v_add_f32_e32 v46, v52, v53
	v_pk_fma_f32 v[44:45], v[50:51], v[50:51], v[44:45]
	s_nop 0
	v_add_f32_e32 v44, v46, v44
	v_add_f32_e32 v44, v44, v45
	ds_bpermute_b32 v45, v38, v44
	s_waitcnt lgkmcnt(0)
	v_add_f32_e32 v44, v44, v45
	ds_bpermute_b32 v45, v39, v44
	s_waitcnt lgkmcnt(0)
	v_add_f32_e32 v44, v44, v45
	ds_bpermute_b32 v45, v40, v44
	s_waitcnt lgkmcnt(0)
	v_add_f32_e32 v44, v44, v45
	ds_bpermute_b32 v45, v41, v44
	s_waitcnt lgkmcnt(0)
	v_add_f32_e32 v44, v44, v45
	ds_bpermute_b32 v45, v42, v44
	s_waitcnt lgkmcnt(0)
	v_add_f32_e32 v44, v44, v45
	ds_bpermute_b32 v45, v43, v44
	s_waitcnt lgkmcnt(0)
	v_add_f32_e32 v44, v44, v45
	v_fmamk_f32 v44, v44, 0x3a800000, v147
	v_rsq_f32_e32 v44, v44
	s_nop 0
	v_pk_mul_f32 v[16:17], v[16:17], v[44:45] op_sel_hi:[1,0]
	v_pk_mul_f32 v[18:19], v[18:19], v[44:45] op_sel_hi:[1,0]
	v_pk_mul_f32 v[20:21], v[20:21], v[44:45] op_sel_hi:[1,0]
	v_pk_mul_f32 v[22:23], v[22:23], v[44:45] op_sel_hi:[1,0]
	v_pk_mul_f32 v[28:29], v[28:29], v[44:45] op_sel_hi:[1,0]
	v_pk_mul_f32 v[30:31], v[30:31], v[44:45] op_sel_hi:[1,0]
	v_pk_mul_f32 v[24:25], v[24:25], v[44:45] op_sel_hi:[1,0]
	v_pk_mul_f32 v[26:27], v[26:27], v[44:45] op_sel_hi:[1,0]
	v_pk_mul_f32 v[16:17], v[0:1], v[16:17]
	v_pk_mul_f32 v[18:19], v[2:3], v[18:19]
	v_pk_mul_f32 v[20:21], v[4:5], v[20:21]
	v_pk_mul_f32 v[22:23], v[6:7], v[22:23]
	v_pk_mul_f32 v[28:29], v[8:9], v[28:29]
	v_pk_mul_f32 v[30:31], v[10:11], v[30:31]
	v_pk_mul_f32 v[24:25], v[12:13], v[24:25]
	v_pk_mul_f32 v[26:27], v[14:15], v[26:27]
	v_cvt_pk_bf16_f32 v16, v16, v17
	v_cvt_pk_bf16_f32 v17, v18, v19
	v_cvt_pk_bf16_f32 v18, v20, v21
	v_cvt_pk_bf16_f32 v19, v22, v23
	v_cvt_pk_bf16_f32 v20, v28, v29
	v_cvt_pk_bf16_f32 v21, v30, v31
	v_cvt_pk_bf16_f32 v22, v24, v25
	v_cvt_pk_bf16_f32 v23, v26, v27
	global_store_dwordx2 v[34:35], v[16:17], off
	global_store_dwordx2 v[34:35], v[18:19], off offset:512
	global_store_dwordx2 v[34:35], v[20:21], off offset:1024
	global_store_dwordx2 v[34:35], v[22:23], off offset:1536
	v_lshl_add_u64 v[34:35], v[34:35], 0, s[18:19]
	s_cbranch_scc1 .LBB0_390

;     __host__ __device__ bool next(int i, Unit& u) const {
;         const long L = (long)i * G + c; if (L >= nwg) return false;
;         int wgid = (int)L; { const int q = nwg / NXCD, r = nwg % NXCD, xcd = wgid % NXCD, off = wgid / NXCD; wgid = (xcd < r ? xcd * (q + 1) : r * (q + 1) + (xcd - r) * q) + off; }
;         const int nig = WGM * nN, gid = wgid / nig, fm = gid * WGM, gsz = (nM - fm) < WGM ? (nM - fm) : WGM;
;         u.pm = fm + ((wgid % nig) % gsz); u.pn = (wgid % nig) / gsz; return true;
; __global__ void __launch_bounds__(512, 2) hybrid_fwd(Params P) {
;     ...
;             pg8::Gemm g{L == 0 ? (const bf16_t*)(ws + WS_H) : (const bf16_t*)POUT, (const bf16_t*)(ws + WS_WIN), MTOK, NINP, DM, DM, DM}; pg8::StaticOrder S; S.init(MTOK, NINP, G, bx);
.LBB0_423:
	s_nop 0
	s_or_b64 exec, exec, s[4:5]
	s_mov_b32 s10, s20
	s_mov_b64 s[4:5], s[58:59]
	s_mov_b32 s52, s69
	s_mov_b32 s53, s2
	s_barrier
	v_mov_b32_e32 v8, v146
	s_cmpk_lt_i32 s53, 0xc00
	s_cselect_b64 s[6:7], -1, 0
	s_cmpk_gt_i32 s53, 0xbff
	v_readfirstlane_b32 s20, v8
	s_cbranch_scc1 .LBB0_425
	s_ashr_i32 s8, s53, 31
	s_lshr_b32 s8, s8, 29
	s_add_i32 s8, s53, s8
	s_ashr_i32 s9, s8, 3
	s_and_b32 s8, s8, -8
	s_sub_i32 s8, s53, s8
	s_cmp_lt_i32 s8, 0
	s_movk_i32 s11, 0x181
	s_cselect_b32 s11, s11, 0x180
	s_mul_i32 s8, s8, s11
	s_add_i32 s8, s8, s9
	s_mul_hi_i32 s9, s8, 0x2aaaaaab
	s_lshr_b32 s11, s9, 31
	s_ashr_i32 s9, s9, 5
	s_add_i32 s9, s9, s11
	s_lshl_b32 s11, s9, 3
	s_mulk_i32 s9, 0xc0
	s_sub_i32 s8, s8, s9
	s_bfe_u32 s9, s8, 0x3001c
	s_add_i32 s9, s8, s9
	s_sext_i32_i16 s12, s9
	s_and_b32 s9, s9, 0xfff8
	s_sub_i32 s8, s8, s9
	s_sext_i32_i16 s8, s8
	s_add_i32 s38, s11, s8
	s_ashr_i32 s36, s12, 3
